# v68 plus WIN rows 0..3583 of layer 1 converted in layer 0's scan (slot free after ph 3); no conversion left in ph 10
# baseline (speedup 1.0000x reference)
.LBB0_76:
	s_mov_b32 s98, 0
	s_mov_b32 s17, 0x1
	s_cmp_eq_u32 s88, 0
	s_cbranch_scc1 .LBB0_81
	s_mov_b32 s17, 0
	s_mov_b32 s99, 0
	s_cmp_eq_u32 s88, 1
	s_cselect_b32 s17, 0x6, s17
	s_cselect_b32 s99, 0x96, s99
	s_cmp_eq_u32 s17, 0
	s_cbranch_scc1 .LBB0_78
	s_cmp_lt_u32 s2, s99
	s_cbranch_scc0 .Lcv_idle

.Lcv_noproc:
	s_mov_b32 s34, 0
	s_sub_u32 s54, s12, 18
	s_cmp_lt_u32 s54, 0x40
	s_cbranch_scc0 .Lcv_noitem
	s_lshl_b32 s54, s54, 10
	s_lshl_b32 s53, s8, 2
	s_add_i32 s53, s53, s11
	s_add_i32 s53, s53, -4
	s_add_i32 s54, s54, s53
	s_mov_b32 s55, 0x3800
	s_cmp_eq_u32 s30, 0
	s_cselect_b32 s55, 0x6700, s55
	s_cmp_lt_u32 s54, s55
	s_cbranch_scc0 .Lcv_noitem
	s_lshl_b32 s61, s30, 12
	s_cmp_lt_u32 s54, 0x1300
	s_cbranch_scc0 .Lcv_j1
	v_readlane_b32 s58, v254, 55
	v_readlane_b32 s59, v254, 56
	v_readlane_b32 s6, v254, 53
	v_readlane_b32 s7, v254, 54
	s_mul_i32 s4, s30, 0x2100000
	s_mov_b32 s60, 0x1080000
	s_mov_b32 s57, 3
	s_nop 1
	s_add_u32 s6, s6, s61
	s_addc_u32 s7, s7, 0
	s_branch .Lcv_jsel

.Lcv_j5:
	s_cmp_lt_u32 s54, 0x5900
	s_cbranch_scc0 .Lcv_j6
	s_sub_u32 s54, s54, 0x4e00
	v_readlane_b32 s58, v254, 51
	v_readlane_b32 s59, v254, 52
	s_mov_b32 s4, 0xb00000
	s_mov_b32 s60, 0xb00000
	s_mov_b32 s57, 2
	s_branch .Lcv_jsel
.Lcv_j6:
	s_sub_u32 s54, s54, 0x5900
	v_readlane_b32 s58, v254, 55
	v_readlane_b32 s59, v254, 56
	v_readlane_b32 s6, v254, 53
	v_readlane_b32 s7, v254, 54
	s_mov_b32 s4, 0x2100000
	s_mov_b32 s60, 0x1080000
	s_mov_b32 s57, 4
	s_nop 1
	s_add_u32 s6, s6, 0x1000
	s_addc_u32 s7, s7, 0
.Lcv_jsel:
	s_nop 1
	s_add_u32 s58, s58, s4
	s_addc_u32 s59, s59, 0
	s_cmp_eq_u32 s57, 1
	s_cbranch_scc1 .Lcv_shb
	s_cmp_eq_u32 s57, 3
	s_cbranch_scc1 .Lcv_shd
	s_cmp_eq_u32 s57, 4
	s_cbranch_scc1 .Lcv_she
	s_and_b32 s55, s54, 63
	s_lshr_b32 s56, s54, 6
	s_lshl_b32 s0, s55, 4
	s_mov_b32 s1, 0x1000
	s_mov_b32 s5, 0xb00
	s_cmp_eq_u32 s57, 0
	s_cselect_b32 s5, 0x400, s5
	s_mov_b32 s35, 0
	s_branch .Lcv_shdone

.Lcv_shd:
	s_lshr_b32 s56, s54, 4
	s_mul_i32 s56, s56, 0xd795
	s_lshr_b32 s56, s56, 20
	s_mul_i32 s55, s56, 0x130
	s_sub_u32 s55, s54, s55
	s_add_i32 s55, s55, 0xe0
	s_branch .Lcv_m2
.Lcv_she:
	s_lshr_b32 s56, s54, 5
	s_mul_i32 s56, s56, 0x12493
	s_lshr_b32 s56, s56, 19
	s_mul_i32 s55, s56, 0xe0
	s_sub_u32 s55, s54, s55
.Lcv_m2:
	s_lshl_b32 s0, s55, 4
	s_cmp_lt_u32 s0, 0xd00
	s_cbranch_scc1 .Lcv_m2done
	s_sub_u32 s1, s0, 0xd00
	s_lshr_b32 s4, s1, 8
	s_and_b32 s5, s1, 0xff
	s_cmp_lt_u32 s4, 4
	s_cbranch_scc0 .Lcv_m2b
	s_lshl_b32 s0, s4, 8
	s_add_i32 s0, s0, s5
	s_add_i32 s0, s0, 0x1900
	s_branch .Lcv_m2done

.LBB0_606:
	s_and_b64 vcc, exec, s[0:1]
	s_cbranch_vccz .LBB0_508
	s_waitcnt vmcnt(0)
	v_lshrrev_b32_e32 v90, 4, v241
	v_bfe_u32 v91, v241, 3, 1
	v_and_b32_e32 v86, 15, v241
	v_lshlrev_b32_e32 v90, 1, v90
	v_lshlrev_b32_e32 v86, 4, v86
	v_add_u32_e32 v92, v90, v91
	v_xor_b32_e32 v91, 1, v91
	v_add_u32_e32 v93, v90, v91
	s_lshl_b32 s0, s10, 5
	v_lshlrev_b32_e32 v89, 2, v92
	v_add_u32_e32 v92, s0, v92
	v_add_u32_e32 v93, s0, v93
	v_add_u32_e32 v89, 0x18000, v89
	v_lshlrev_b32_e32 v87, 2, v92
	v_lshlrev_b32_e32 v88, 2, v93
	v_mov_b32_e32 v0, 0
	v_mov_b32_e32 v1, 0
	v_mov_b32_e32 v2, 0
	v_mov_b32_e32 v3, 0
	v_mov_b32_e32 v4, 0
	v_mov_b32_e32 v5, 0
	v_mov_b32_e32 v6, 0
	v_mov_b32_e32 v7, 0
	s_waitcnt lgkmcnt(0)
	s_barrier
	s_mov_b32 s4, 0
	s_nop 0
	s_nop 0
